# stack: + compression-MLP LDS read pairing, + counted LDS waits in the second merge pass loop
# baseline (speedup 1.0000x reference)
.LBB0_242:
	v_mov_b32_e32 v2, v0
	v_mov_b32_e32 v3, v0
	v_mov_b32_e32 v4, v0
	v_mov_b32_e32 v5, v0
	v_mov_b32_e32 v6, v0
	v_mov_b32_e32 v7, v0
	v_mov_b32_e32 v8, v0
	v_mov_b32_e32 v9, v0
	v_mov_b32_e32 v10, v0
	v_mov_b32_e32 v11, v0
	v_mov_b32_e32 v12, v0
	v_mov_b32_e32 v13, v0
	v_mov_b32_e32 v14, v0
	v_mov_b32_e32 v15, v0
	v_mov_b32_e32 v1, v0
	v_mov_b64_e32 v[16:17], v[14:15]
	v_mov_b64_e32 v[14:15], v[12:13]
	v_mov_b64_e32 v[12:13], v[10:11]
	v_mov_b64_e32 v[10:11], v[8:9]
	v_mov_b64_e32 v[8:9], v[6:7]
	v_mov_b64_e32 v[6:7], v[4:5]
	v_mov_b64_e32 v[4:5], v[2:3]
	v_mov_b64_e32 v[2:3], v[0:1]
	s_waitcnt lgkmcnt(0)
	s_barrier
	s_and_saveexec_b64 s[10:11], s[0:1]
	s_cbranch_execz .LBB0_258
	ds_read2_b32 v[76:77], v130 offset1:68
	ds_read2_b32 v[248:249], v130 offset0:136 offset1:204
	s_waitcnt lgkmcnt(1)
	v_mfma_f32_32x32x2_f32 v[2:17], v76, v135, 0
	v_mfma_f32_32x32x2_f32 v[2:17], v77, v136, v[2:17]
	s_waitcnt lgkmcnt(0)
	v_mfma_f32_32x32x2_f32 v[2:17], v248, v137, v[2:17]
	v_mfma_f32_32x32x2_f32 v[2:17], v249, v138, v[2:17]
	s_or_b64 exec, exec, s[10:11]
	s_and_saveexec_b64 s[10:11], s[0:1]
	s_cbranch_execnz .LBB0_259

.LBB0_245:
	ds_read2_b32 v[76:77], v132 offset1:68
	ds_read2_b32 v[248:249], v132 offset0:136 offset1:204
	s_waitcnt lgkmcnt(1)
	v_mfma_f32_32x32x2_f32 v[2:17], v76, v143, v[2:17]
	v_mfma_f32_32x32x2_f32 v[2:17], v77, v144, v[2:17]
	s_waitcnt lgkmcnt(0)
	v_mfma_f32_32x32x2_f32 v[2:17], v248, v145, v[2:17]
	v_mfma_f32_32x32x2_f32 v[2:17], v249, v146, v[2:17]
	s_or_b64 exec, exec, s[10:11]
	s_and_saveexec_b64 s[10:11], s[0:1]
	s_cbranch_execnz .LBB0_261

.LBB0_247:
	ds_read2_b32 v[76:77], v204 offset1:68
	ds_read2_b32 v[248:249], v204 offset0:136 offset1:204
	s_waitcnt lgkmcnt(1)
	v_mfma_f32_32x32x2_f32 v[2:17], v76, v151, v[2:17]
	v_mfma_f32_32x32x2_f32 v[2:17], v77, v152, v[2:17]
	s_waitcnt lgkmcnt(0)
	v_mfma_f32_32x32x2_f32 v[2:17], v248, v153, v[2:17]
	v_mfma_f32_32x32x2_f32 v[2:17], v249, v154, v[2:17]
	s_or_b64 exec, exec, s[10:11]
	s_and_saveexec_b64 s[10:11], s[4:5]
	s_cbranch_execnz .LBB0_263

.LBB0_249:
	ds_read2_b32 v[76:77], v206 offset1:68
	ds_read2_b32 v[248:249], v206 offset0:136 offset1:204
	s_waitcnt lgkmcnt(1)
	v_mfma_f32_32x32x2_f32 v[2:17], v76, v159, v[2:17]
	v_mfma_f32_32x32x2_f32 v[2:17], v77, v160, v[2:17]
	s_waitcnt lgkmcnt(0)
	v_mfma_f32_32x32x2_f32 v[2:17], v248, v161, v[2:17]
	v_mfma_f32_32x32x2_f32 v[2:17], v249, v166, v[2:17]
	s_or_b64 exec, exec, s[10:11]
	s_and_saveexec_b64 s[10:11], s[4:5]
	s_cbranch_execnz .LBB0_265

.LBB0_251:
	v_add_u32_e32 v1, 0x800, v207
	ds_read2_b32 v[76:77], v1 offset0:32 offset1:100
	ds_read2_b32 v[248:249], v1 offset0:168 offset1:236
	s_waitcnt lgkmcnt(1)
	v_mfma_f32_32x32x2_f32 v[2:17], v76, v171, v[2:17]
	v_mfma_f32_32x32x2_f32 v[2:17], v77, v172, v[2:17]
	s_waitcnt lgkmcnt(0)
	v_mfma_f32_32x32x2_f32 v[2:17], v248, v173, v[2:17]
	v_mfma_f32_32x32x2_f32 v[2:17], v249, v174, v[2:17]
	s_or_b64 exec, exec, s[10:11]
	s_and_saveexec_b64 s[10:11], s[6:7]
	s_cbranch_execnz .LBB0_267

.LBB0_259:
	ds_read2_b32 v[76:77], v131 offset1:68
	ds_read2_b32 v[248:249], v131 offset0:136 offset1:204
	s_waitcnt lgkmcnt(1)
	v_mfma_f32_32x32x2_f32 v[2:17], v76, v139, v[2:17]
	v_mfma_f32_32x32x2_f32 v[2:17], v77, v140, v[2:17]
	s_waitcnt lgkmcnt(0)
	v_mfma_f32_32x32x2_f32 v[2:17], v248, v141, v[2:17]
	v_mfma_f32_32x32x2_f32 v[2:17], v249, v142, v[2:17]
	s_or_b64 exec, exec, s[10:11]
	s_and_saveexec_b64 s[10:11], s[0:1]
	s_cbranch_execnz .LBB0_245

.LBB0_261:
	ds_read2_b32 v[76:77], v133 offset1:68
	ds_read2_b32 v[248:249], v133 offset0:136 offset1:204
	s_waitcnt lgkmcnt(1)
	v_mfma_f32_32x32x2_f32 v[2:17], v76, v147, v[2:17]
	v_mfma_f32_32x32x2_f32 v[2:17], v77, v148, v[2:17]
	s_waitcnt lgkmcnt(0)
	v_mfma_f32_32x32x2_f32 v[2:17], v248, v149, v[2:17]
	v_mfma_f32_32x32x2_f32 v[2:17], v249, v150, v[2:17]
	s_or_b64 exec, exec, s[10:11]
	s_and_saveexec_b64 s[10:11], s[4:5]
	s_cbranch_execnz .LBB0_247

.LBB0_263:
	ds_read2_b32 v[76:77], v205 offset1:68
	ds_read2_b32 v[248:249], v205 offset0:136 offset1:204
	s_waitcnt lgkmcnt(1)
	v_mfma_f32_32x32x2_f32 v[2:17], v76, v155, v[2:17]
	v_mfma_f32_32x32x2_f32 v[2:17], v77, v156, v[2:17]
	s_waitcnt lgkmcnt(0)
	v_mfma_f32_32x32x2_f32 v[2:17], v248, v157, v[2:17]
	v_mfma_f32_32x32x2_f32 v[2:17], v249, v158, v[2:17]
	s_or_b64 exec, exec, s[10:11]
	s_and_saveexec_b64 s[10:11], s[4:5]
	s_cbranch_execnz .LBB0_249

.LBB0_265:
	ds_read2_b32 v[76:77], v207 offset1:68
	ds_read2_b32 v[248:249], v207 offset0:136 offset1:204
	s_waitcnt lgkmcnt(1)
	v_mfma_f32_32x32x2_f32 v[2:17], v76, v167, v[2:17]
	v_mfma_f32_32x32x2_f32 v[2:17], v77, v168, v[2:17]
	s_waitcnt lgkmcnt(0)
	v_mfma_f32_32x32x2_f32 v[2:17], v248, v169, v[2:17]
	v_mfma_f32_32x32x2_f32 v[2:17], v249, v170, v[2:17]
	s_or_b64 exec, exec, s[10:11]
	s_and_saveexec_b64 s[10:11], s[6:7]
	s_cbranch_execnz .LBB0_251

.LBB0_273:
	v_add_u32_e32 v1, 0x4400, v207
	ds_read2_b32 v[76:77], v1 offset1:68
	ds_read2_b32 v[248:249], v1 offset0:136 offset1:204
	s_waitcnt lgkmcnt(1)
	v_mfma_f32_32x32x2_f32 v[2:17], v76, v98, v[2:17]
	v_mfma_f32_32x32x2_f32 v[2:17], v77, v99, v[2:17]
	s_waitcnt lgkmcnt(0)
	v_mfma_f32_32x32x2_f32 v[2:17], v248, v100, v[2:17]
	v_mfma_f32_32x32x2_f32 v[2:17], v249, v101, v[2:17]
	s_branch .LBB0_239

.LBB0_1173:
	s_mul_hi_u32 s12, s35, 0xaaaaaaab
	s_lshr_b32 s16, s12, 1
	s_mul_i32 s16, s16, 0x24000
	v_subrev_u32_e32 v114, s16, v152
	v_subrev_u32_e32 v115, s16, v153
	v_add_u32_e32 v139, s29, v141
	s_waitcnt lgkmcnt(7)
	v_mfma_f32_16x16x32_bf16 v[110:113], v[18:21], v[2:5], v[110:113]
	v_add_u32_e32 v115, v139, v115
	v_add_u32_e32 v114, v139, v114
	ds_read_b128 v[122:125], v115 offset:16384
	ds_read_b128 v[118:121], v115 offset:18432
	ds_read_b128 v[126:129], v114 offset:16384
	ds_read_b128 v[114:117], v114 offset:18432
	s_waitcnt lgkmcnt(9)
	v_mfma_f32_16x16x32_bf16 v[106:109], v[26:29], v[2:5], v[106:109]
	s_cmp_ge_i32 s21, s17
	s_cselect_b64 s[12:13], -1, 0
	s_or_b64 s[12:13], s[14:15], s[12:13]
	s_waitcnt lgkmcnt(7)
	v_mfma_f32_16x16x32_bf16 v[102:105], v[34:37], v[2:5], v[102:105]
	s_and_b64 vcc, exec, s[12:13]
	s_mov_b64 s[12:13], -1
	s_waitcnt lgkmcnt(6)
	v_mfma_f32_16x16x32_bf16 v[98:101], v[38:41], v[2:5], v[98:101]
	v_mfma_f32_16x16x32_bf16 v[94:97], v[18:21], v[6:9], v[94:97]
	v_mfma_f32_16x16x32_bf16 v[90:93], v[26:29], v[6:9], v[90:93]
	v_mfma_f32_16x16x32_bf16 v[86:89], v[34:37], v[6:9], v[86:89]
	v_mfma_f32_16x16x32_bf16 v[82:85], v[38:41], v[6:9], v[82:85]
	v_mfma_f32_16x16x32_bf16 v[110:113], v[22:25], v[10:13], v[110:113]
	v_mfma_f32_16x16x32_bf16 v[106:109], v[30:33], v[10:13], v[106:109]
	s_waitcnt lgkmcnt(5)
	v_mfma_f32_16x16x32_bf16 v[102:105], v[42:45], v[10:13], v[102:105]
	s_waitcnt lgkmcnt(4)
	v_mfma_f32_16x16x32_bf16 v[98:101], v[46:49], v[10:13], v[98:101]
	v_mfma_f32_16x16x32_bf16 v[94:97], v[22:25], v[14:17], v[94:97]
	v_mfma_f32_16x16x32_bf16 v[90:93], v[30:33], v[14:17], v[90:93]
	v_mfma_f32_16x16x32_bf16 v[86:89], v[42:45], v[14:17], v[86:89]
	v_mfma_f32_16x16x32_bf16 v[82:85], v[46:49], v[14:17], v[82:85]
	s_cbranch_vccnz .LBB0_1175
	s_waitcnt vmcnt(6)
	s_mov_b64 s[12:13], 0

.LBB0_1196:
	v_mfma_f32_16x16x32_bf16 v[78:81], v[18:21], v[122:125], v[78:81]
	s_andn2_b64 vcc, exec, s[12:13]
	v_mfma_f32_16x16x32_bf16 v[74:77], v[26:29], v[122:125], v[74:77]
	v_mfma_f32_16x16x32_bf16 v[70:73], v[34:37], v[122:125], v[70:73]
	v_mfma_f32_16x16x32_bf16 v[66:69], v[38:41], v[122:125], v[66:69]
	v_mfma_f32_16x16x32_bf16 v[62:65], v[18:21], v[118:121], v[62:65]
	v_mfma_f32_16x16x32_bf16 v[58:61], v[26:29], v[118:121], v[58:61]
	v_mfma_f32_16x16x32_bf16 v[54:57], v[34:37], v[118:121], v[54:57]
	v_mfma_f32_16x16x32_bf16 v[50:53], v[38:41], v[118:121], v[50:53]
	v_mfma_f32_16x16x32_bf16 v[78:81], v[22:25], v[126:129], v[78:81]
	v_mfma_f32_16x16x32_bf16 v[74:77], v[30:33], v[126:129], v[74:77]
	v_mfma_f32_16x16x32_bf16 v[70:73], v[42:45], v[126:129], v[70:73]
	v_mfma_f32_16x16x32_bf16 v[66:69], v[46:49], v[126:129], v[66:69]
	v_mfma_f32_16x16x32_bf16 v[62:65], v[22:25], v[114:117], v[62:65]
	v_mfma_f32_16x16x32_bf16 v[58:61], v[30:33], v[114:117], v[58:61]
	v_mfma_f32_16x16x32_bf16 v[54:57], v[42:45], v[114:117], v[54:57]
	v_mfma_f32_16x16x32_bf16 v[50:53], v[46:49], v[114:117], v[50:53]
	s_cbranch_vccnz .LBB0_1198
	v_subrev_u32_e32 v26, s14, v146
	v_subrev_u32_e32 v34, s14, v147
	v_subrev_u32_e32 v18, s14, v148
	v_subrev_u32_e32 v27, s14, v149
	v_subrev_u32_e32 v35, s14, v150
	v_subrev_u32_e32 v19, s14, v151
	v_add_u32_e32 v19, v139, v19
	v_add_u32_e32 v22, v139, v18
	v_add_u32_e32 v27, v139, v27
	v_add_u32_e32 v30, v139, v26
	v_add_u32_e32 v38, v139, v35
	v_add_u32_e32 v46, v139, v34
	ds_read_b128 v[18:21], v19
	ds_read_b128 v[22:25], v22
	ds_read_b128 v[26:29], v27
	ds_read_b128 v[30:33], v30
	ds_read_b128 v[34:37], v38
	ds_read_b128 v[38:41], v38 offset:2048
	ds_read_b128 v[42:45], v46
	ds_read_b128 v[46:49], v46 offset:2048
